# phase-5 gate epilogue: six per-group s_waitcnt vmcnt(0) placed right behind a store relaxed to vmcnt(1) (the protected gate loads are older than that store); on v070
# speedup vs baseline: 1.0162x; 1.0021x over previous
.LBB0_659:
	v_ashrrev_i32_e32 v185, 31, v184
	v_lshlrev_b64 v[2:3], 12, v[184:185]
	v_ashrrev_i32_e32 v187, 31, v186
	v_lshl_add_u64 v[2:3], s[38:39], 0, v[2:3]
	v_lshlrev_b64 v[140:141], 1, v[186:187]
	v_lshl_add_u64 v[2:3], v[2:3], 0, v[140:141]
	global_load_dwordx4 v[144:147], v[2:3], off offset:2048
	global_load_dwordx4 v[148:151], v[2:3], off offset:2112
	v_or_b32_e32 v142, 16, v184
	v_ashrrev_i32_e32 v143, 31, v142
	v_lshlrev_b64 v[132:133], 12, v[142:143]
	v_lshl_add_u64 v[132:133], s[38:39], 0, v[132:133]
	v_lshl_add_u64 v[132:133], v[132:133], 0, v[140:141]
	global_load_dwordx4 v[136:139], v[132:133], off offset:2048
	s_nop 0
	global_load_dwordx4 v[132:135], v[132:133], off offset:2112
	v_or_b32_e32 v2, v186, v197
	v_ashrrev_i32_e32 v3, 31, v2
	v_lshlrev_b64 v[2:3], 1, v[2:3]
	s_and_b64 vcc, exec, s[4:5]
	s_mov_b32 s17, s44
	s_mov_b32 s54, s46
	s_mov_b64 s[56:57], s[50:51]
	s_mov_b64 s[52:53], s[48:49]
	s_waitcnt vmcnt(0)
	v_lshlrev_b32_e32 v1, 16, v144
	v_and_b32_e32 v143, 0xffff0000, v144
	v_lshlrev_b32_e32 v144, 16, v145
	v_and_b32_e32 v145, 0xffff0000, v145
	v_lshlrev_b32_e32 v152, 16, v146
	v_and_b32_e32 v146, 0xffff0000, v146
	v_lshlrev_b32_e32 v153, 16, v147
	v_and_b32_e32 v147, 0xffff0000, v147
	v_lshlrev_b32_e32 v154, 16, v148
	v_and_b32_e32 v148, 0xffff0000, v148
	v_lshlrev_b32_e32 v155, 16, v149
	v_and_b32_e32 v149, 0xffff0000, v149
	v_max_f32_e32 v144, v144, v144
	v_max_f32_e32 v145, v145, v145
	v_max_f32_e32 v152, v152, v152
	v_max_f32_e32 v146, v146, v146
	v_max_f32_e32 v147, v147, v147
	v_max_f32_e32 v148, v148, v148
	v_max_f32_e32 v156, v149, v149
	v_max_f32_e32 v144, 0xc2700000, v144
	v_max_f32_e32 v145, 0xc2700000, v145
	v_max_f32_e32 v149, 0xc2700000, v152
	v_max_f32_e32 v146, 0xc2700000, v146
	v_max_f32_e32 v153, v153, v153
	v_max_f32_e32 v147, 0xc2700000, v147
	v_max_f32_e32 v148, 0xc2700000, v148
	v_mul_f32_e32 v144, 0xbfb8aa3b, v144
	v_mul_f32_e32 v145, 0xbfb8aa3b, v145
	v_mul_f32_e32 v149, 0xbfb8aa3b, v149
	v_mul_f32_e32 v146, 0xbfb8aa3b, v146
	v_max_f32_e32 v154, v154, v154
	v_max_f32_e32 v152, 0xc2700000, v153
	v_mul_f32_e32 v147, 0xbfb8aa3b, v147
	v_mul_f32_e32 v148, 0xbfb8aa3b, v148
	v_exp_f32_e32 v144, v144
	v_exp_f32_e32 v145, v145
	v_exp_f32_e32 v149, v149
	v_exp_f32_e32 v146, v146
	v_max_f32_e32 v153, 0xc2700000, v154
	v_mul_f32_e32 v152, 0xbfb8aa3b, v152
	v_exp_f32_e32 v147, v147
	v_exp_f32_e32 v148, v148
	v_mul_f32_e32 v153, 0xbfb8aa3b, v153
	v_exp_f32_e32 v152, v152
	v_exp_f32_e32 v153, v153
	v_max_f32_e32 v1, v1, v1
	v_max_f32_e32 v143, v143, v143
	v_add_f32_e32 v154, 1.0, v144
	v_add_f32_e32 v157, 1.0, v145
	v_add_f32_e32 v149, 1.0, v149
	v_add_f32_e32 v158, 1.0, v146
	v_max_f32_e32 v1, 0xc2700000, v1
	v_max_f32_e32 v143, 0xc2700000, v143
	v_add_f32_e32 v159, 1.0, v147
	v_add_f32_e32 v161, 1.0, v148
	v_rcp_f32_e32 v146, v154
	v_rcp_f32_e32 v147, v157
	v_rcp_f32_e32 v148, v149
	v_rcp_f32_e32 v149, v158
	v_mul_f32_e32 v1, 0xbfb8aa3b, v1
	v_mul_f32_e32 v143, 0xbfb8aa3b, v143
	v_add_f32_e32 v152, 1.0, v152
	v_exp_f32_e32 v1, v1
	v_exp_f32_e32 v143, v143
	v_add_f32_e32 v160, 1.0, v153
	v_rcp_f32_e32 v152, v152
	v_rcp_f32_e32 v153, v159
	v_max_f32_e32 v155, v155, v155
	v_pk_mul_f32 v[130:131], v[130:131], v[146:147]
	v_pk_mul_f32 v[124:125], v[124:125], v[148:149]
	v_max_f32_e32 v155, 0xc2700000, v155
	v_cvt_pk_bf16_f32 v130, v130, v131
	v_cvt_pk_bf16_f32 v131, v124, v125
	v_max_f32_e32 v124, 0xc2700000, v156
	v_add_f32_e32 v1, 1.0, v1
	v_add_f32_e32 v143, 1.0, v143
	v_pk_mul_f32 v[126:127], v[126:127], v[152:153]
	v_mul_f32_e32 v125, 0xbfb8aa3b, v155
	v_mul_f32_e32 v124, 0xbfb8aa3b, v124
	v_rcp_f32_e32 v144, v1
	v_rcp_f32_e32 v145, v143
	v_cvt_pk_bf16_f32 v143, v126, v127
	v_exp_f32_e32 v125, v125
	v_exp_f32_e32 v126, v124
	v_pk_mul_f32 v[128:129], v[128:129], v[144:145]
	v_and_b32_e32 v127, 0xffff0000, v150
	v_add_f32_e32 v124, 1.0, v125
	v_add_f32_e32 v125, 1.0, v126
	v_lshlrev_b32_e32 v126, 16, v150
	v_cvt_pk_bf16_f32 v1, v128, v129
	v_max_f32_e32 v126, v126, v126
	v_max_f32_e32 v127, v127, v127
	v_lshlrev_b32_e32 v128, 16, v151
	v_and_b32_e32 v129, 0xffff0000, v151
	v_max_f32_e32 v126, 0xc2700000, v126
	v_max_f32_e32 v127, 0xc2700000, v127
	v_max_f32_e32 v128, v128, v128
	v_max_f32_e32 v129, v129, v129
	v_mul_f32_e32 v126, 0xbfb8aa3b, v126
	v_mul_f32_e32 v127, 0xbfb8aa3b, v127
	v_max_f32_e32 v128, 0xc2700000, v128
	v_max_f32_e32 v129, 0xc2700000, v129
	v_exp_f32_e32 v126, v126
	v_exp_f32_e32 v127, v127
	v_mul_f32_e32 v128, 0xbfb8aa3b, v128
	v_mul_f32_e32 v129, 0xbfb8aa3b, v129
	v_exp_f32_e32 v128, v128
	v_exp_f32_e32 v129, v129
	v_rcp_f32_e32 v154, v160
	v_rcp_f32_e32 v155, v161
	v_add_f32_e32 v126, 1.0, v126
	v_add_f32_e32 v127, 1.0, v127
	v_rcp_f32_e32 v124, v124
	v_rcp_f32_e32 v125, v125
	v_rcp_f32_e32 v126, v126
	v_rcp_f32_e32 v127, v127
	v_add_f32_e32 v128, 1.0, v128
	v_add_f32_e32 v129, 1.0, v129
	v_rcp_f32_e32 v128, v128
	v_rcp_f32_e32 v129, v129
	v_pk_mul_f32 v[120:121], v[120:121], v[154:155]
	v_pk_mul_f32 v[122:123], v[122:123], v[124:125]
	v_pk_mul_f32 v[116:117], v[116:117], v[126:127]
	v_cvt_pk_bf16_f32 v120, v120, v121
	v_pk_mul_f32 v[118:119], v[118:119], v[128:129]
	v_cvt_pk_bf16_f32 v121, v122, v123
	v_cvt_pk_bf16_f32 v122, v116, v117
	v_cndmask_b32_e64 v116, v1, v120, s[2:3]
	v_mov_b32_e32 v124, 0
	v_cvt_pk_bf16_f32 v123, v118, v119
	v_mov_b32_e32 v125, 0
	v_mov_b32_dpp v124, v116 row_ror:8 row_mask:0xf bank_mask:0xf
	v_cndmask_b32_e64 v116, v130, v121, s[2:3]
	v_mov_b32_e32 v127, 0
	v_cndmask_b32_e64 v117, v131, v122, s[2:3]
	v_mov_b32_dpp v125, v116 row_ror:8 row_mask:0xf bank_mask:0xf
	v_cndmask_b32_e64 v116, v143, v123, s[2:3]
	v_mov_b32_e32 v126, 0
	v_cndmask_b32_e64 v120, v120, v124, s[2:3]
	v_mov_b32_dpp v127, v116 row_ror:8 row_mask:0xf bank_mask:0xf
	v_cndmask_b32_e64 v116, v124, v1, s[2:3]
	v_add_u32_e32 v1, -8, v184
	v_cndmask_b32_e64 v124, v1, v184, s[2:3]
	v_mov_b32_dpp v126, v117 row_ror:8 row_mask:0xf bank_mask:0xf
	v_cndmask_b32_e64 v117, v125, v130, s[2:3]
	v_cndmask_b32_e64 v121, v121, v125, s[2:3]
	v_ashrrev_i32_e32 v125, 31, v124
	v_lshlrev_b64 v[124:125], 11, v[124:125]
	v_lshl_add_u64 v[124:125], s[68:69], 0, v[124:125]
	v_cndmask_b32_e64 v119, v127, v143, s[2:3]
	v_cndmask_b32_e64 v118, v126, v131, s[2:3]
	v_lshl_add_u64 v[124:125], v[124:125], 0, v[2:3]
	v_add_u32_e32 v1, 8, v184
	global_store_dwordx4 v[124:125], v[116:119], off
	v_or_b32_e32 v124, 32, v184
	v_cndmask_b32_e64 v123, v123, v127, s[2:3]
	v_cndmask_b32_e64 v116, v184, v1, s[2:3]
	v_ashrrev_i32_e32 v117, 31, v116
	v_lshlrev_b64 v[116:117], 11, v[116:117]
	v_lshl_add_u64 v[116:117], s[68:69], 0, v[116:117]
	v_lshlrev_b32_e32 v118, 16, v136
	v_cndmask_b32_e64 v122, v122, v126, s[2:3]
	v_lshl_add_u64 v[116:117], v[116:117], 0, v[2:3]
	v_ashrrev_i32_e32 v125, 31, v124
	v_max_f32_e32 v118, v118, v118
	v_and_b32_e32 v119, 0xffff0000, v136
	global_store_dwordx4 v[116:117], v[120:123], off
	v_lshlrev_b64 v[116:117], 12, v[124:125]
	v_max_f32_e32 v118, 0xc2700000, v118
	v_max_f32_e32 v119, v119, v119
	v_lshl_add_u64 v[116:117], s[38:39], 0, v[116:117]
	v_max_f32_e32 v119, 0xc2700000, v119
	v_mul_f32_e32 v118, 0xbfb8aa3b, v118
	v_lshl_add_u64 v[116:117], v[116:117], 0, v[140:141]
	v_exp_f32_e32 v125, v118
	v_mul_f32_e32 v118, 0xbfb8aa3b, v119
	v_exp_f32_e32 v127, v118
	global_load_dwordx4 v[120:123], v[116:117], off offset:2048
	s_nop 0
	global_load_dwordx4 v[116:119], v[116:117], off offset:2112
	v_add_f32_e32 v125, 1.0, v125
	v_rcp_f32_e32 v126, v125
	v_add_f32_e32 v125, 1.0, v127
	v_lshlrev_b32_e32 v127, 16, v137
	v_max_f32_e32 v127, v127, v127
	v_and_b32_e32 v128, 0xffff0000, v137
	v_max_f32_e32 v127, 0xc2700000, v127
	v_max_f32_e32 v128, v128, v128
	v_max_f32_e32 v128, 0xc2700000, v128
	v_mul_f32_e32 v127, 0xbfb8aa3b, v127
	v_exp_f32_e32 v129, v127
	v_mul_f32_e32 v127, 0xbfb8aa3b, v128
	v_exp_f32_e32 v130, v127
	v_rcp_f32_e32 v127, v125
	v_add_f32_e32 v125, 1.0, v129
	v_lshlrev_b32_e32 v129, 16, v138
	v_rcp_f32_e32 v128, v125
	v_add_f32_e32 v125, 1.0, v130
	v_max_f32_e32 v129, v129, v129
	v_and_b32_e32 v130, 0xffff0000, v138
	v_max_f32_e32 v129, 0xc2700000, v129
	v_max_f32_e32 v130, v130, v130
	v_max_f32_e32 v130, 0xc2700000, v130
	v_mul_f32_e32 v129, 0xbfb8aa3b, v129
	v_exp_f32_e32 v131, v129
	v_mul_f32_e32 v129, 0xbfb8aa3b, v130
	v_exp_f32_e32 v136, v129
	v_rcp_f32_e32 v129, v125
	v_add_f32_e32 v125, 1.0, v131
	v_lshlrev_b32_e32 v131, 16, v139
	v_rcp_f32_e32 v130, v125
	v_add_f32_e32 v125, 1.0, v136
	v_max_f32_e32 v131, v131, v131
	v_and_b32_e32 v136, 0xffff0000, v139
	v_max_f32_e32 v131, 0xc2700000, v131
	v_max_f32_e32 v136, v136, v136
	v_max_f32_e32 v136, 0xc2700000, v136
	v_mul_f32_e32 v131, 0xbfb8aa3b, v131
	v_exp_f32_e32 v137, v131
	v_mul_f32_e32 v131, 0xbfb8aa3b, v136
	v_exp_f32_e32 v138, v131
	v_rcp_f32_e32 v131, v125
	v_add_f32_e32 v125, 1.0, v137
	v_rcp_f32_e32 v136, v125
	v_add_f32_e32 v125, 1.0, v138
	v_rcp_f32_e32 v137, v125
	v_pk_mul_f32 v[108:109], v[108:109], v[130:131]
	v_pk_mul_f32 v[112:113], v[112:113], v[126:127]
	v_cvt_pk_bf16_f32 v127, v108, v109
	v_pk_mul_f32 v[110:111], v[110:111], v[136:137]
	v_lshlrev_b32_e32 v108, 16, v132
	v_and_b32_e32 v109, 0xffff0000, v132
	v_pk_mul_f32 v[114:115], v[114:115], v[128:129]
	v_cvt_pk_bf16_f32 v125, v112, v113
	v_max_f32_e32 v108, v108, v108
	v_max_f32_e32 v109, v109, v109
	v_cvt_pk_bf16_f32 v128, v110, v111
	v_lshlrev_b32_e32 v110, 16, v133
	v_and_b32_e32 v111, 0xffff0000, v133
	v_lshlrev_b32_e32 v112, 16, v134
	v_and_b32_e32 v113, 0xffff0000, v134
	v_cvt_pk_bf16_f32 v126, v114, v115
	v_max_f32_e32 v108, 0xc2700000, v108
	v_max_f32_e32 v109, 0xc2700000, v109
	v_max_f32_e32 v110, v110, v110
	v_max_f32_e32 v111, v111, v111
	v_max_f32_e32 v112, v112, v112
	v_max_f32_e32 v113, v113, v113
	v_lshlrev_b32_e32 v114, 16, v135
	v_and_b32_e32 v115, 0xffff0000, v135
	v_mul_f32_e32 v108, 0xbfb8aa3b, v108
	v_mul_f32_e32 v109, 0xbfb8aa3b, v109
	v_max_f32_e32 v110, 0xc2700000, v110
	v_max_f32_e32 v111, 0xc2700000, v111
	v_max_f32_e32 v112, 0xc2700000, v112
	v_max_f32_e32 v113, 0xc2700000, v113
	v_max_f32_e32 v114, v114, v114
	v_max_f32_e32 v115, v115, v115
	v_exp_f32_e32 v108, v108
	v_exp_f32_e32 v109, v109
	v_mul_f32_e32 v110, 0xbfb8aa3b, v110
	v_mul_f32_e32 v111, 0xbfb8aa3b, v111
	v_mul_f32_e32 v112, 0xbfb8aa3b, v112
	v_mul_f32_e32 v113, 0xbfb8aa3b, v113
	v_max_f32_e32 v114, 0xc2700000, v114
	v_max_f32_e32 v115, 0xc2700000, v115
	v_exp_f32_e32 v110, v110
	v_exp_f32_e32 v111, v111
	v_exp_f32_e32 v112, v112
	v_exp_f32_e32 v113, v113
	v_mul_f32_e32 v114, 0xbfb8aa3b, v114
	v_mul_f32_e32 v115, 0xbfb8aa3b, v115
	v_exp_f32_e32 v114, v114
	v_exp_f32_e32 v115, v115
	v_add_f32_e32 v108, 1.0, v108
	v_add_f32_e32 v109, 1.0, v109
	v_rcp_f32_e32 v108, v108
	v_rcp_f32_e32 v109, v109
	v_add_f32_e32 v110, 1.0, v110
	v_add_f32_e32 v111, 1.0, v111
	v_add_f32_e32 v112, 1.0, v112
	v_add_f32_e32 v113, 1.0, v113
	v_rcp_f32_e32 v110, v110
	v_rcp_f32_e32 v111, v111
	v_rcp_f32_e32 v112, v112
	v_rcp_f32_e32 v113, v113
	v_add_f32_e32 v114, 1.0, v114
	v_add_f32_e32 v115, 1.0, v115
	v_rcp_f32_e32 v114, v114
	v_rcp_f32_e32 v115, v115
	v_pk_mul_f32 v[104:105], v[104:105], v[108:109]
	v_pk_mul_f32 v[106:107], v[106:107], v[110:111]
	v_pk_mul_f32 v[100:101], v[100:101], v[112:113]
	v_cvt_pk_bf16_f32 v104, v104, v105
	v_pk_mul_f32 v[102:103], v[102:103], v[114:115]
	v_cvt_pk_bf16_f32 v105, v106, v107
	v_cvt_pk_bf16_f32 v106, v100, v101
	v_cndmask_b32_e64 v100, v125, v104, s[2:3]
	v_mov_b32_e32 v108, 0
	v_cvt_pk_bf16_f32 v107, v102, v103
	v_mov_b32_e32 v109, 0
	v_mov_b32_dpp v108, v100 row_ror:8 row_mask:0xf bank_mask:0xf
	v_cndmask_b32_e64 v100, v126, v105, s[2:3]
	v_mov_b32_e32 v111, 0
	v_cndmask_b32_e64 v101, v127, v106, s[2:3]
	v_mov_b32_dpp v109, v100 row_ror:8 row_mask:0xf bank_mask:0xf
	v_cndmask_b32_e64 v100, v128, v107, s[2:3]
	v_mov_b32_e32 v110, 0
	v_cndmask_b32_e64 v104, v104, v108, s[2:3]
	v_mov_b32_dpp v111, v100 row_ror:8 row_mask:0xf bank_mask:0xf
	v_cndmask_b32_e64 v100, v108, v125, s[2:3]
	v_cndmask_b32_e64 v108, v1, v142, s[2:3]
	v_mov_b32_dpp v110, v101 row_ror:8 row_mask:0xf bank_mask:0xf
	v_cndmask_b32_e64 v101, v109, v126, s[2:3]
	v_cndmask_b32_e64 v105, v105, v109, s[2:3]
	v_ashrrev_i32_e32 v109, 31, v108
	v_lshlrev_b64 v[108:109], 11, v[108:109]
	v_lshl_add_u64 v[108:109], s[68:69], 0, v[108:109]
	v_cndmask_b32_e64 v103, v111, v128, s[2:3]
	v_cndmask_b32_e64 v102, v110, v127, s[2:3]
	v_lshl_add_u64 v[108:109], v[108:109], 0, v[2:3]
	v_add_u32_e32 v1, 24, v184
	global_store_dwordx4 v[108:109], v[100:103], off
	v_or_b32_e32 v108, 48, v184
	v_cndmask_b32_e64 v107, v107, v111, s[2:3]
	v_cndmask_b32_e64 v100, v142, v1, s[2:3]
	v_ashrrev_i32_e32 v101, 31, v100
	v_lshlrev_b64 v[100:101], 11, v[100:101]
	v_lshl_add_u64 v[100:101], s[68:69], 0, v[100:101]
	s_waitcnt vmcnt(1)
	v_lshlrev_b32_e32 v102, 16, v120
	v_cndmask_b32_e64 v106, v106, v110, s[2:3]
	v_lshl_add_u64 v[100:101], v[100:101], 0, v[2:3]
	v_ashrrev_i32_e32 v109, 31, v108
	v_max_f32_e32 v102, v102, v102
	v_and_b32_e32 v103, 0xffff0000, v120
	global_store_dwordx4 v[100:101], v[104:107], off
	v_lshlrev_b64 v[100:101], 12, v[108:109]
	v_max_f32_e32 v102, 0xc2700000, v102
	v_max_f32_e32 v103, v103, v103
	v_lshl_add_u64 v[100:101], s[38:39], 0, v[100:101]
	v_max_f32_e32 v103, 0xc2700000, v103
	v_mul_f32_e32 v102, 0xbfb8aa3b, v102
	v_lshl_add_u64 v[100:101], v[100:101], 0, v[140:141]
	v_exp_f32_e32 v109, v102
	v_mul_f32_e32 v102, 0xbfb8aa3b, v103
	v_exp_f32_e32 v111, v102
	global_load_dwordx4 v[104:107], v[100:101], off offset:2048
	s_nop 0
	global_load_dwordx4 v[100:103], v[100:101], off offset:2112
	v_add_f32_e32 v109, 1.0, v109
	v_rcp_f32_e32 v110, v109
	v_add_f32_e32 v109, 1.0, v111
	v_lshlrev_b32_e32 v111, 16, v121
	v_max_f32_e32 v111, v111, v111
	v_and_b32_e32 v112, 0xffff0000, v121
	v_max_f32_e32 v111, 0xc2700000, v111
	v_max_f32_e32 v112, v112, v112
	v_max_f32_e32 v112, 0xc2700000, v112
	v_mul_f32_e32 v111, 0xbfb8aa3b, v111
	v_exp_f32_e32 v113, v111
	v_mul_f32_e32 v111, 0xbfb8aa3b, v112
	v_exp_f32_e32 v114, v111
	v_rcp_f32_e32 v111, v109
	v_add_f32_e32 v109, 1.0, v113
	v_lshlrev_b32_e32 v113, 16, v122
	v_rcp_f32_e32 v112, v109
	v_add_f32_e32 v109, 1.0, v114
	v_max_f32_e32 v113, v113, v113
	v_and_b32_e32 v114, 0xffff0000, v122
	v_max_f32_e32 v113, 0xc2700000, v113
	v_max_f32_e32 v114, v114, v114
	v_max_f32_e32 v114, 0xc2700000, v114
	v_mul_f32_e32 v113, 0xbfb8aa3b, v113
	v_exp_f32_e32 v115, v113
	v_mul_f32_e32 v113, 0xbfb8aa3b, v114
	v_exp_f32_e32 v120, v113
	v_rcp_f32_e32 v113, v109
	v_add_f32_e32 v109, 1.0, v115
	v_lshlrev_b32_e32 v115, 16, v123
	v_rcp_f32_e32 v114, v109
	v_add_f32_e32 v109, 1.0, v120
	v_max_f32_e32 v115, v115, v115
	v_and_b32_e32 v120, 0xffff0000, v123
	v_max_f32_e32 v115, 0xc2700000, v115
	v_max_f32_e32 v120, v120, v120
	v_max_f32_e32 v120, 0xc2700000, v120
	v_mul_f32_e32 v115, 0xbfb8aa3b, v115
	v_exp_f32_e32 v121, v115
	v_mul_f32_e32 v115, 0xbfb8aa3b, v120
	v_exp_f32_e32 v122, v115
	v_rcp_f32_e32 v115, v109
	v_add_f32_e32 v109, 1.0, v121
	v_rcp_f32_e32 v120, v109
	v_add_f32_e32 v109, 1.0, v122
	v_rcp_f32_e32 v121, v109
	v_pk_mul_f32 v[92:93], v[92:93], v[114:115]
	v_pk_mul_f32 v[96:97], v[96:97], v[110:111]
	v_cvt_pk_bf16_f32 v111, v92, v93
	v_pk_mul_f32 v[94:95], v[94:95], v[120:121]
	v_lshlrev_b32_e32 v92, 16, v116
	v_and_b32_e32 v93, 0xffff0000, v116
	v_pk_mul_f32 v[98:99], v[98:99], v[112:113]
	v_cvt_pk_bf16_f32 v109, v96, v97
	v_max_f32_e32 v92, v92, v92
	v_max_f32_e32 v93, v93, v93
	v_cvt_pk_bf16_f32 v112, v94, v95
	v_lshlrev_b32_e32 v94, 16, v117
	v_and_b32_e32 v95, 0xffff0000, v117
	v_lshlrev_b32_e32 v96, 16, v118
	v_and_b32_e32 v97, 0xffff0000, v118
	v_cvt_pk_bf16_f32 v110, v98, v99
	v_max_f32_e32 v92, 0xc2700000, v92
	v_max_f32_e32 v93, 0xc2700000, v93
	v_max_f32_e32 v94, v94, v94
	v_max_f32_e32 v95, v95, v95
	v_max_f32_e32 v96, v96, v96
	v_max_f32_e32 v97, v97, v97
	v_lshlrev_b32_e32 v98, 16, v119
	v_and_b32_e32 v99, 0xffff0000, v119
	v_mul_f32_e32 v92, 0xbfb8aa3b, v92
	v_mul_f32_e32 v93, 0xbfb8aa3b, v93
	v_max_f32_e32 v94, 0xc2700000, v94
	v_max_f32_e32 v95, 0xc2700000, v95
	v_max_f32_e32 v96, 0xc2700000, v96
	v_max_f32_e32 v97, 0xc2700000, v97
	v_max_f32_e32 v98, v98, v98
	v_max_f32_e32 v99, v99, v99
	v_exp_f32_e32 v92, v92
	v_exp_f32_e32 v93, v93
	v_mul_f32_e32 v94, 0xbfb8aa3b, v94
	v_mul_f32_e32 v95, 0xbfb8aa3b, v95
	v_mul_f32_e32 v96, 0xbfb8aa3b, v96
	v_mul_f32_e32 v97, 0xbfb8aa3b, v97
	v_max_f32_e32 v98, 0xc2700000, v98
	v_max_f32_e32 v99, 0xc2700000, v99
	v_exp_f32_e32 v94, v94
	v_exp_f32_e32 v95, v95
	v_exp_f32_e32 v96, v96
	v_exp_f32_e32 v97, v97
	v_mul_f32_e32 v98, 0xbfb8aa3b, v98
	v_mul_f32_e32 v99, 0xbfb8aa3b, v99
	v_exp_f32_e32 v98, v98
	v_exp_f32_e32 v99, v99
	v_add_f32_e32 v92, 1.0, v92
	v_add_f32_e32 v93, 1.0, v93
	v_rcp_f32_e32 v92, v92
	v_rcp_f32_e32 v93, v93
	v_add_f32_e32 v94, 1.0, v94
	v_add_f32_e32 v95, 1.0, v95
	v_add_f32_e32 v96, 1.0, v96
	v_add_f32_e32 v97, 1.0, v97
	v_rcp_f32_e32 v94, v94
	v_rcp_f32_e32 v95, v95
	v_rcp_f32_e32 v96, v96
	v_rcp_f32_e32 v97, v97
	v_add_f32_e32 v98, 1.0, v98
	v_add_f32_e32 v99, 1.0, v99
	v_rcp_f32_e32 v98, v98
	v_rcp_f32_e32 v99, v99
	v_pk_mul_f32 v[88:89], v[88:89], v[92:93]
	v_pk_mul_f32 v[90:91], v[90:91], v[94:95]
	v_pk_mul_f32 v[84:85], v[84:85], v[96:97]
	v_cvt_pk_bf16_f32 v88, v88, v89
	v_pk_mul_f32 v[86:87], v[86:87], v[98:99]
	v_cvt_pk_bf16_f32 v89, v90, v91
	v_cvt_pk_bf16_f32 v90, v84, v85
	v_cndmask_b32_e64 v84, v109, v88, s[2:3]
	v_mov_b32_e32 v92, 0
	v_cvt_pk_bf16_f32 v91, v86, v87
	v_mov_b32_e32 v93, 0
	v_mov_b32_dpp v92, v84 row_ror:8 row_mask:0xf bank_mask:0xf
	v_cndmask_b32_e64 v84, v110, v89, s[2:3]
	v_mov_b32_e32 v95, 0
	v_cndmask_b32_e64 v85, v111, v90, s[2:3]
	v_mov_b32_dpp v93, v84 row_ror:8 row_mask:0xf bank_mask:0xf
	v_cndmask_b32_e64 v84, v112, v91, s[2:3]
	v_mov_b32_e32 v94, 0
	v_cndmask_b32_e64 v88, v88, v92, s[2:3]
	v_mov_b32_dpp v95, v84 row_ror:8 row_mask:0xf bank_mask:0xf
	v_cndmask_b32_e64 v84, v92, v109, s[2:3]
	v_cndmask_b32_e64 v92, v1, v124, s[2:3]
	v_mov_b32_dpp v94, v85 row_ror:8 row_mask:0xf bank_mask:0xf
	v_cndmask_b32_e64 v85, v93, v110, s[2:3]
	v_cndmask_b32_e64 v89, v89, v93, s[2:3]
	v_ashrrev_i32_e32 v93, 31, v92
	v_lshlrev_b64 v[92:93], 11, v[92:93]
	v_lshl_add_u64 v[92:93], s[68:69], 0, v[92:93]
	v_cndmask_b32_e64 v87, v95, v112, s[2:3]
	v_cndmask_b32_e64 v86, v94, v111, s[2:3]
	v_lshl_add_u64 v[92:93], v[92:93], 0, v[2:3]
	v_add_u32_e32 v1, 40, v184
	global_store_dwordx4 v[92:93], v[84:87], off
	v_add_u32_e32 v92, 0x80, v184
	v_cndmask_b32_e64 v91, v91, v95, s[2:3]
	v_cndmask_b32_e64 v84, v124, v1, s[2:3]
	v_ashrrev_i32_e32 v85, 31, v84
	v_lshlrev_b64 v[84:85], 11, v[84:85]
	v_lshl_add_u64 v[84:85], s[68:69], 0, v[84:85]
	s_waitcnt vmcnt(1)
	v_lshlrev_b32_e32 v86, 16, v104
	v_cndmask_b32_e64 v90, v90, v94, s[2:3]
	v_lshl_add_u64 v[84:85], v[84:85], 0, v[2:3]
	v_ashrrev_i32_e32 v93, 31, v92
	v_max_f32_e32 v86, v86, v86
	v_and_b32_e32 v87, 0xffff0000, v104
	global_store_dwordx4 v[84:85], v[88:91], off
	v_lshlrev_b64 v[84:85], 12, v[92:93]
	v_max_f32_e32 v86, 0xc2700000, v86
	v_max_f32_e32 v87, v87, v87
	v_lshl_add_u64 v[84:85], s[38:39], 0, v[84:85]
	v_max_f32_e32 v87, 0xc2700000, v87
	v_mul_f32_e32 v86, 0xbfb8aa3b, v86
	v_lshl_add_u64 v[84:85], v[84:85], 0, v[140:141]
	v_exp_f32_e32 v93, v86
	v_mul_f32_e32 v86, 0xbfb8aa3b, v87
	v_exp_f32_e32 v95, v86
	global_load_dwordx4 v[88:91], v[84:85], off offset:2048
	s_nop 0
	global_load_dwordx4 v[84:87], v[84:85], off offset:2112
	v_add_f32_e32 v93, 1.0, v93
	v_rcp_f32_e32 v94, v93
	v_add_f32_e32 v93, 1.0, v95
	v_lshlrev_b32_e32 v95, 16, v105
	v_max_f32_e32 v95, v95, v95
	v_and_b32_e32 v96, 0xffff0000, v105
	v_max_f32_e32 v95, 0xc2700000, v95
	v_max_f32_e32 v96, v96, v96
	v_max_f32_e32 v96, 0xc2700000, v96
	v_mul_f32_e32 v95, 0xbfb8aa3b, v95
	v_exp_f32_e32 v97, v95
	v_mul_f32_e32 v95, 0xbfb8aa3b, v96
	v_exp_f32_e32 v98, v95
	v_rcp_f32_e32 v95, v93
	v_add_f32_e32 v93, 1.0, v97
	v_lshlrev_b32_e32 v97, 16, v106
	v_rcp_f32_e32 v96, v93
	v_add_f32_e32 v93, 1.0, v98
	v_max_f32_e32 v97, v97, v97
	v_and_b32_e32 v98, 0xffff0000, v106
	v_max_f32_e32 v97, 0xc2700000, v97
	v_max_f32_e32 v98, v98, v98
	v_max_f32_e32 v98, 0xc2700000, v98
	v_mul_f32_e32 v97, 0xbfb8aa3b, v97
	v_exp_f32_e32 v99, v97
	v_mul_f32_e32 v97, 0xbfb8aa3b, v98
	v_exp_f32_e32 v104, v97
	v_rcp_f32_e32 v97, v93
	v_add_f32_e32 v93, 1.0, v99
	v_lshlrev_b32_e32 v99, 16, v107
	v_rcp_f32_e32 v98, v93
	v_add_f32_e32 v93, 1.0, v104
	v_max_f32_e32 v99, v99, v99
	v_and_b32_e32 v104, 0xffff0000, v107
	v_max_f32_e32 v99, 0xc2700000, v99
	v_max_f32_e32 v104, v104, v104
	v_max_f32_e32 v104, 0xc2700000, v104
	v_mul_f32_e32 v99, 0xbfb8aa3b, v99
	v_exp_f32_e32 v105, v99
	v_mul_f32_e32 v99, 0xbfb8aa3b, v104
	v_exp_f32_e32 v106, v99
	v_rcp_f32_e32 v99, v93
	v_add_f32_e32 v93, 1.0, v105
	v_rcp_f32_e32 v104, v93
	v_add_f32_e32 v93, 1.0, v106
	v_rcp_f32_e32 v105, v93
	v_pk_mul_f32 v[76:77], v[76:77], v[98:99]
	v_pk_mul_f32 v[80:81], v[80:81], v[94:95]
	v_cvt_pk_bf16_f32 v95, v76, v77
	v_pk_mul_f32 v[78:79], v[78:79], v[104:105]
	v_lshlrev_b32_e32 v76, 16, v100
	v_and_b32_e32 v77, 0xffff0000, v100
	v_pk_mul_f32 v[82:83], v[82:83], v[96:97]
	v_cvt_pk_bf16_f32 v93, v80, v81
	v_max_f32_e32 v76, v76, v76
	v_max_f32_e32 v77, v77, v77
	v_cvt_pk_bf16_f32 v96, v78, v79
	v_lshlrev_b32_e32 v78, 16, v101
	v_and_b32_e32 v79, 0xffff0000, v101
	v_lshlrev_b32_e32 v80, 16, v102
	v_and_b32_e32 v81, 0xffff0000, v102
	v_cvt_pk_bf16_f32 v94, v82, v83
	v_max_f32_e32 v76, 0xc2700000, v76
	v_max_f32_e32 v77, 0xc2700000, v77
	v_max_f32_e32 v78, v78, v78
	v_max_f32_e32 v79, v79, v79
	v_max_f32_e32 v80, v80, v80
	v_max_f32_e32 v81, v81, v81
	v_lshlrev_b32_e32 v82, 16, v103
	v_and_b32_e32 v83, 0xffff0000, v103
	v_mul_f32_e32 v76, 0xbfb8aa3b, v76
	v_mul_f32_e32 v77, 0xbfb8aa3b, v77
	v_max_f32_e32 v78, 0xc2700000, v78
	v_max_f32_e32 v79, 0xc2700000, v79
	v_max_f32_e32 v80, 0xc2700000, v80
	v_max_f32_e32 v81, 0xc2700000, v81
	v_max_f32_e32 v82, v82, v82
	v_max_f32_e32 v83, v83, v83
	v_exp_f32_e32 v76, v76
	v_exp_f32_e32 v77, v77
	v_mul_f32_e32 v78, 0xbfb8aa3b, v78
	v_mul_f32_e32 v79, 0xbfb8aa3b, v79
	v_mul_f32_e32 v80, 0xbfb8aa3b, v80
	v_mul_f32_e32 v81, 0xbfb8aa3b, v81
	v_max_f32_e32 v82, 0xc2700000, v82
	v_max_f32_e32 v83, 0xc2700000, v83
	v_exp_f32_e32 v78, v78
	v_exp_f32_e32 v79, v79
	v_exp_f32_e32 v80, v80
	v_exp_f32_e32 v81, v81
	v_mul_f32_e32 v82, 0xbfb8aa3b, v82
	v_mul_f32_e32 v83, 0xbfb8aa3b, v83
	v_exp_f32_e32 v82, v82
	v_exp_f32_e32 v83, v83
	v_add_f32_e32 v76, 1.0, v76
	v_add_f32_e32 v77, 1.0, v77
	v_rcp_f32_e32 v76, v76
	v_rcp_f32_e32 v77, v77
	v_add_f32_e32 v78, 1.0, v78
	v_add_f32_e32 v79, 1.0, v79
	v_add_f32_e32 v80, 1.0, v80
	v_add_f32_e32 v81, 1.0, v81
	v_rcp_f32_e32 v78, v78
	v_rcp_f32_e32 v79, v79
	v_rcp_f32_e32 v80, v80
	v_rcp_f32_e32 v81, v81
	v_add_f32_e32 v82, 1.0, v82
	v_add_f32_e32 v83, 1.0, v83
	v_rcp_f32_e32 v82, v82
	v_rcp_f32_e32 v83, v83
	v_pk_mul_f32 v[72:73], v[72:73], v[76:77]
	v_pk_mul_f32 v[74:75], v[74:75], v[78:79]
	v_pk_mul_f32 v[68:69], v[68:69], v[80:81]
	v_cvt_pk_bf16_f32 v72, v72, v73
	v_pk_mul_f32 v[70:71], v[70:71], v[82:83]
	v_cvt_pk_bf16_f32 v73, v74, v75
	v_cvt_pk_bf16_f32 v74, v68, v69
	v_cndmask_b32_e64 v68, v93, v72, s[2:3]
	v_mov_b32_e32 v76, 0
	v_cvt_pk_bf16_f32 v75, v70, v71
	v_mov_b32_e32 v77, 0
	v_mov_b32_dpp v76, v68 row_ror:8 row_mask:0xf bank_mask:0xf
	v_cndmask_b32_e64 v68, v94, v73, s[2:3]
	v_mov_b32_e32 v79, 0
	v_cndmask_b32_e64 v69, v95, v74, s[2:3]
	v_mov_b32_dpp v77, v68 row_ror:8 row_mask:0xf bank_mask:0xf
	v_cndmask_b32_e64 v68, v96, v75, s[2:3]
	v_mov_b32_e32 v78, 0
	v_cndmask_b32_e64 v72, v72, v76, s[2:3]
	v_mov_b32_dpp v79, v68 row_ror:8 row_mask:0xf bank_mask:0xf
	v_cndmask_b32_e64 v68, v76, v93, s[2:3]
	v_cndmask_b32_e64 v76, v1, v108, s[2:3]
	v_mov_b32_dpp v78, v69 row_ror:8 row_mask:0xf bank_mask:0xf
	v_cndmask_b32_e64 v69, v77, v94, s[2:3]
	v_cndmask_b32_e64 v73, v73, v77, s[2:3]
	v_ashrrev_i32_e32 v77, 31, v76
	v_lshlrev_b64 v[76:77], 11, v[76:77]
	v_lshl_add_u64 v[76:77], s[68:69], 0, v[76:77]
	v_cndmask_b32_e64 v71, v79, v96, s[2:3]
	v_cndmask_b32_e64 v70, v78, v95, s[2:3]
	v_lshl_add_u64 v[76:77], v[76:77], 0, v[2:3]
	v_add_u32_e32 v1, 56, v184
	global_store_dwordx4 v[76:77], v[68:71], off
	v_add_u32_e32 v76, 0x90, v184
	v_cndmask_b32_e64 v75, v75, v79, s[2:3]
	v_cndmask_b32_e64 v68, v108, v1, s[2:3]
	v_ashrrev_i32_e32 v69, 31, v68
	v_lshlrev_b64 v[68:69], 11, v[68:69]
	v_lshl_add_u64 v[68:69], s[68:69], 0, v[68:69]
	v_cndmask_b32_e64 v74, v74, v78, s[2:3]
	v_lshl_add_u64 v[68:69], v[68:69], 0, v[2:3]
	v_ashrrev_i32_e32 v77, 31, v76
	s_waitcnt vmcnt(1)
	v_and_b32_e32 v70, 0xffff0000, v88
	global_store_dwordx4 v[68:69], v[72:75], off
	v_lshlrev_b64 v[68:69], 12, v[76:77]
	v_max_f32_e32 v70, v70, v70
	v_lshl_add_u64 v[68:69], s[38:39], 0, v[68:69]
	v_max_f32_e32 v70, 0xc2700000, v70
	v_lshl_add_u64 v[68:69], v[68:69], 0, v[140:141]
	v_mul_f32_e32 v70, 0xbfb8aa3b, v70
	v_exp_f32_e32 v77, v70
	global_load_dwordx4 v[72:75], v[68:69], off offset:2048
	s_nop 0
	global_load_dwordx4 v[68:71], v[68:69], off offset:2112
	v_lshlrev_b32_e32 v1, 16, v88
	v_max_f32_e32 v1, v1, v1
	v_max_f32_e32 v1, 0xc2700000, v1
	v_mul_f32_e32 v1, 0xbfb8aa3b, v1
	v_exp_f32_e32 v1, v1
	v_and_b32_e32 v79, 0xffff0000, v89
	v_max_f32_e32 v79, v79, v79
	v_max_f32_e32 v79, 0xc2700000, v79
	v_add_f32_e32 v1, 1.0, v1
	v_rcp_f32_e32 v78, v1
	v_add_f32_e32 v1, 1.0, v77
	v_lshlrev_b32_e32 v77, 16, v89
	v_max_f32_e32 v77, v77, v77
	v_max_f32_e32 v77, 0xc2700000, v77
	v_mul_f32_e32 v77, 0xbfb8aa3b, v77
	v_exp_f32_e32 v77, v77
	v_mul_f32_e32 v79, 0xbfb8aa3b, v79
	v_exp_f32_e32 v81, v79
	v_rcp_f32_e32 v79, v1
	v_add_f32_e32 v1, 1.0, v77
	v_lshlrev_b32_e32 v77, 16, v90
	v_rcp_f32_e32 v80, v1
	v_add_f32_e32 v1, 1.0, v81
	v_max_f32_e32 v77, v77, v77
	v_and_b32_e32 v81, 0xffff0000, v90
	v_max_f32_e32 v77, 0xc2700000, v77
	v_max_f32_e32 v81, v81, v81
	v_max_f32_e32 v81, 0xc2700000, v81
	v_mul_f32_e32 v77, 0xbfb8aa3b, v77
	v_exp_f32_e32 v77, v77
	v_mul_f32_e32 v81, 0xbfb8aa3b, v81
	v_exp_f32_e32 v83, v81
	v_rcp_f32_e32 v81, v1
	v_add_f32_e32 v1, 1.0, v77
	v_lshlrev_b32_e32 v77, 16, v91
	v_rcp_f32_e32 v82, v1
	v_add_f32_e32 v1, 1.0, v83
	v_max_f32_e32 v77, v77, v77
	v_and_b32_e32 v83, 0xffff0000, v91
	v_max_f32_e32 v77, 0xc2700000, v77
	v_max_f32_e32 v83, v83, v83
	v_max_f32_e32 v83, 0xc2700000, v83
	v_mul_f32_e32 v77, 0xbfb8aa3b, v77
	v_exp_f32_e32 v77, v77
	v_mul_f32_e32 v83, 0xbfb8aa3b, v83
	v_exp_f32_e32 v89, v83
	v_rcp_f32_e32 v83, v1
	v_add_f32_e32 v1, 1.0, v77
	v_rcp_f32_e32 v88, v1
	v_add_f32_e32 v1, 1.0, v89
	v_rcp_f32_e32 v89, v1
	v_pk_mul_f32 v[60:61], v[60:61], v[82:83]
	v_pk_mul_f32 v[64:65], v[64:65], v[78:79]
	v_cvt_pk_bf16_f32 v78, v60, v61
	v_pk_mul_f32 v[62:63], v[62:63], v[88:89]
	v_lshlrev_b32_e32 v60, 16, v84
	v_and_b32_e32 v61, 0xffff0000, v84
	v_pk_mul_f32 v[66:67], v[66:67], v[80:81]
	v_cvt_pk_bf16_f32 v1, v64, v65
	v_max_f32_e32 v60, v60, v60
	v_max_f32_e32 v61, v61, v61
	v_cvt_pk_bf16_f32 v79, v62, v63
	v_lshlrev_b32_e32 v62, 16, v85
	v_and_b32_e32 v63, 0xffff0000, v85
	v_lshlrev_b32_e32 v64, 16, v86
	v_and_b32_e32 v65, 0xffff0000, v86
	v_cvt_pk_bf16_f32 v77, v66, v67
	v_max_f32_e32 v60, 0xc2700000, v60
	v_max_f32_e32 v61, 0xc2700000, v61
	v_max_f32_e32 v62, v62, v62
	v_max_f32_e32 v63, v63, v63
	v_max_f32_e32 v64, v64, v64
	v_max_f32_e32 v65, v65, v65
	v_lshlrev_b32_e32 v66, 16, v87
	v_and_b32_e32 v67, 0xffff0000, v87
	v_mul_f32_e32 v60, 0xbfb8aa3b, v60
	v_mul_f32_e32 v61, 0xbfb8aa3b, v61
	v_max_f32_e32 v62, 0xc2700000, v62
	v_max_f32_e32 v63, 0xc2700000, v63
	v_max_f32_e32 v64, 0xc2700000, v64
	v_max_f32_e32 v65, 0xc2700000, v65
	v_max_f32_e32 v66, v66, v66
	v_max_f32_e32 v67, v67, v67
	v_exp_f32_e32 v60, v60
	v_exp_f32_e32 v61, v61
	v_mul_f32_e32 v62, 0xbfb8aa3b, v62
	v_mul_f32_e32 v63, 0xbfb8aa3b, v63
	v_mul_f32_e32 v64, 0xbfb8aa3b, v64
	v_mul_f32_e32 v65, 0xbfb8aa3b, v65
	v_max_f32_e32 v66, 0xc2700000, v66
	v_max_f32_e32 v67, 0xc2700000, v67
	v_exp_f32_e32 v62, v62
	v_exp_f32_e32 v63, v63
	v_exp_f32_e32 v64, v64
	v_exp_f32_e32 v65, v65
	v_mul_f32_e32 v66, 0xbfb8aa3b, v66
	v_mul_f32_e32 v67, 0xbfb8aa3b, v67
	v_exp_f32_e32 v66, v66
	v_exp_f32_e32 v67, v67
	v_add_f32_e32 v60, 1.0, v60
	v_add_f32_e32 v61, 1.0, v61
	v_rcp_f32_e32 v60, v60
	v_rcp_f32_e32 v61, v61
	v_add_f32_e32 v62, 1.0, v62
	v_add_f32_e32 v63, 1.0, v63
	v_add_f32_e32 v64, 1.0, v64
	v_add_f32_e32 v65, 1.0, v65
	v_rcp_f32_e32 v62, v62
	v_rcp_f32_e32 v63, v63
	v_rcp_f32_e32 v64, v64
	v_rcp_f32_e32 v65, v65
	v_add_f32_e32 v66, 1.0, v66
	v_add_f32_e32 v67, 1.0, v67
	v_rcp_f32_e32 v66, v66
	v_rcp_f32_e32 v67, v67
	v_pk_mul_f32 v[56:57], v[56:57], v[60:61]
	v_pk_mul_f32 v[58:59], v[58:59], v[62:63]
	v_pk_mul_f32 v[52:53], v[52:53], v[64:65]
	v_cvt_pk_bf16_f32 v56, v56, v57
	v_pk_mul_f32 v[54:55], v[54:55], v[66:67]
	v_cvt_pk_bf16_f32 v57, v58, v59
	v_cvt_pk_bf16_f32 v58, v52, v53
	v_cndmask_b32_e64 v52, v1, v56, s[2:3]
	v_mov_b32_e32 v60, 0
	v_cvt_pk_bf16_f32 v59, v54, v55
	v_mov_b32_e32 v61, 0
	v_mov_b32_dpp v60, v52 row_ror:8 row_mask:0xf bank_mask:0xf
	v_cndmask_b32_e64 v52, v77, v57, s[2:3]
	v_mov_b32_e32 v63, 0
	v_cndmask_b32_e64 v53, v78, v58, s[2:3]
	v_mov_b32_dpp v61, v52 row_ror:8 row_mask:0xf bank_mask:0xf
	v_cndmask_b32_e64 v52, v79, v59, s[2:3]
	v_mov_b32_e32 v62, 0
	v_cndmask_b32_e64 v56, v56, v60, s[2:3]
	v_mov_b32_dpp v63, v52 row_ror:8 row_mask:0xf bank_mask:0xf
	v_cndmask_b32_e64 v52, v60, v1, s[2:3]
	v_add_u32_e32 v1, 0x78, v184
	v_cndmask_b32_e64 v60, v1, v92, s[2:3]
	v_mov_b32_dpp v62, v53 row_ror:8 row_mask:0xf bank_mask:0xf
	v_cndmask_b32_e64 v53, v61, v77, s[2:3]
	v_cndmask_b32_e64 v57, v57, v61, s[2:3]
	v_ashrrev_i32_e32 v61, 31, v60
	v_lshlrev_b64 v[60:61], 11, v[60:61]
	v_lshl_add_u64 v[60:61], s[68:69], 0, v[60:61]
	v_cndmask_b32_e64 v55, v63, v79, s[2:3]
	v_cndmask_b32_e64 v54, v62, v78, s[2:3]
	v_lshl_add_u64 v[60:61], v[60:61], 0, v[2:3]
	v_add_u32_e32 v1, 0x88, v184
	global_store_dwordx4 v[60:61], v[52:55], off
	v_add_u32_e32 v60, 0xa0, v184
	v_cndmask_b32_e64 v59, v59, v63, s[2:3]
	v_cndmask_b32_e64 v52, v92, v1, s[2:3]
	v_ashrrev_i32_e32 v53, 31, v52
	v_lshlrev_b64 v[52:53], 11, v[52:53]
	v_lshl_add_u64 v[52:53], s[68:69], 0, v[52:53]
	s_waitcnt vmcnt(1)
	v_lshlrev_b32_e32 v54, 16, v72
	v_cndmask_b32_e64 v58, v58, v62, s[2:3]
	v_lshl_add_u64 v[52:53], v[52:53], 0, v[2:3]
	v_ashrrev_i32_e32 v61, 31, v60
	v_max_f32_e32 v54, v54, v54
	v_and_b32_e32 v55, 0xffff0000, v72
	global_store_dwordx4 v[52:53], v[56:59], off
	v_lshlrev_b64 v[52:53], 12, v[60:61]
	v_max_f32_e32 v54, 0xc2700000, v54
	v_max_f32_e32 v55, v55, v55
	v_lshl_add_u64 v[52:53], s[38:39], 0, v[52:53]
	v_max_f32_e32 v55, 0xc2700000, v55
	v_mul_f32_e32 v54, 0xbfb8aa3b, v54
	v_lshl_add_u64 v[52:53], v[52:53], 0, v[140:141]
	v_exp_f32_e32 v61, v54
	v_mul_f32_e32 v54, 0xbfb8aa3b, v55
	v_exp_f32_e32 v63, v54
	global_load_dwordx4 v[56:59], v[52:53], off offset:2048
	s_nop 0
	global_load_dwordx4 v[52:55], v[52:53], off offset:2112
	v_add_f32_e32 v61, 1.0, v61
	v_rcp_f32_e32 v62, v61
	v_add_f32_e32 v61, 1.0, v63
	v_lshlrev_b32_e32 v63, 16, v73
	v_max_f32_e32 v63, v63, v63
	v_and_b32_e32 v64, 0xffff0000, v73
	v_max_f32_e32 v63, 0xc2700000, v63
	v_max_f32_e32 v64, v64, v64
	v_max_f32_e32 v64, 0xc2700000, v64
	v_mul_f32_e32 v63, 0xbfb8aa3b, v63
	v_exp_f32_e32 v65, v63
	v_mul_f32_e32 v63, 0xbfb8aa3b, v64
	v_exp_f32_e32 v66, v63
	v_rcp_f32_e32 v63, v61
	v_add_f32_e32 v61, 1.0, v65
	v_lshlrev_b32_e32 v65, 16, v74
	v_rcp_f32_e32 v64, v61
	v_add_f32_e32 v61, 1.0, v66
	v_max_f32_e32 v65, v65, v65
	v_and_b32_e32 v66, 0xffff0000, v74
	v_max_f32_e32 v65, 0xc2700000, v65
	v_max_f32_e32 v66, v66, v66
	v_max_f32_e32 v66, 0xc2700000, v66
	v_mul_f32_e32 v65, 0xbfb8aa3b, v65
	v_exp_f32_e32 v67, v65
	v_mul_f32_e32 v65, 0xbfb8aa3b, v66
	v_exp_f32_e32 v72, v65
	v_rcp_f32_e32 v65, v61
	v_add_f32_e32 v61, 1.0, v67
	v_lshlrev_b32_e32 v67, 16, v75
	v_rcp_f32_e32 v66, v61
	v_add_f32_e32 v61, 1.0, v72
	v_max_f32_e32 v67, v67, v67
	v_and_b32_e32 v72, 0xffff0000, v75
	v_max_f32_e32 v67, 0xc2700000, v67
	v_max_f32_e32 v72, v72, v72
	v_max_f32_e32 v72, 0xc2700000, v72
	v_mul_f32_e32 v67, 0xbfb8aa3b, v67
	v_exp_f32_e32 v73, v67
	v_mul_f32_e32 v67, 0xbfb8aa3b, v72
	v_exp_f32_e32 v74, v67
	v_rcp_f32_e32 v67, v61
	v_add_f32_e32 v61, 1.0, v73
	v_rcp_f32_e32 v72, v61
	v_add_f32_e32 v61, 1.0, v74
	v_rcp_f32_e32 v73, v61
	v_pk_mul_f32 v[44:45], v[44:45], v[66:67]
	v_pk_mul_f32 v[48:49], v[48:49], v[62:63]
	v_cvt_pk_bf16_f32 v63, v44, v45
	v_pk_mul_f32 v[46:47], v[46:47], v[72:73]
	v_lshlrev_b32_e32 v44, 16, v68
	v_and_b32_e32 v45, 0xffff0000, v68
	v_pk_mul_f32 v[50:51], v[50:51], v[64:65]
	v_cvt_pk_bf16_f32 v61, v48, v49
	v_max_f32_e32 v44, v44, v44
	v_max_f32_e32 v45, v45, v45
	v_cvt_pk_bf16_f32 v64, v46, v47
	v_lshlrev_b32_e32 v46, 16, v69
	v_and_b32_e32 v47, 0xffff0000, v69
	v_lshlrev_b32_e32 v48, 16, v70
	v_and_b32_e32 v49, 0xffff0000, v70
	v_cvt_pk_bf16_f32 v62, v50, v51
	v_max_f32_e32 v44, 0xc2700000, v44
	v_max_f32_e32 v45, 0xc2700000, v45
	v_max_f32_e32 v46, v46, v46
	v_max_f32_e32 v47, v47, v47
	v_max_f32_e32 v48, v48, v48
	v_max_f32_e32 v49, v49, v49
	v_lshlrev_b32_e32 v50, 16, v71
	v_and_b32_e32 v51, 0xffff0000, v71
	v_mul_f32_e32 v44, 0xbfb8aa3b, v44
	v_mul_f32_e32 v45, 0xbfb8aa3b, v45
	v_max_f32_e32 v46, 0xc2700000, v46
	v_max_f32_e32 v47, 0xc2700000, v47
	v_max_f32_e32 v48, 0xc2700000, v48
	v_max_f32_e32 v49, 0xc2700000, v49
	v_max_f32_e32 v50, v50, v50
	v_max_f32_e32 v51, v51, v51
	v_exp_f32_e32 v44, v44
	v_exp_f32_e32 v45, v45
	v_mul_f32_e32 v46, 0xbfb8aa3b, v46
	v_mul_f32_e32 v47, 0xbfb8aa3b, v47
	v_mul_f32_e32 v48, 0xbfb8aa3b, v48
	v_mul_f32_e32 v49, 0xbfb8aa3b, v49
	v_max_f32_e32 v50, 0xc2700000, v50
	v_max_f32_e32 v51, 0xc2700000, v51
	v_exp_f32_e32 v46, v46
	v_exp_f32_e32 v47, v47
	v_exp_f32_e32 v48, v48
	v_exp_f32_e32 v49, v49
	v_mul_f32_e32 v50, 0xbfb8aa3b, v50
	v_mul_f32_e32 v51, 0xbfb8aa3b, v51
	v_exp_f32_e32 v50, v50
	v_exp_f32_e32 v51, v51
	v_add_f32_e32 v44, 1.0, v44
	v_add_f32_e32 v45, 1.0, v45
	v_rcp_f32_e32 v44, v44
	v_rcp_f32_e32 v45, v45
	v_add_f32_e32 v46, 1.0, v46
	v_add_f32_e32 v47, 1.0, v47
	v_add_f32_e32 v48, 1.0, v48
	v_add_f32_e32 v49, 1.0, v49
	v_rcp_f32_e32 v46, v46
	v_rcp_f32_e32 v47, v47
	v_rcp_f32_e32 v48, v48
	v_rcp_f32_e32 v49, v49
	v_add_f32_e32 v50, 1.0, v50
	v_add_f32_e32 v51, 1.0, v51
	v_rcp_f32_e32 v50, v50
	v_rcp_f32_e32 v51, v51
	v_pk_mul_f32 v[40:41], v[40:41], v[44:45]
	v_pk_mul_f32 v[42:43], v[42:43], v[46:47]
	v_pk_mul_f32 v[36:37], v[36:37], v[48:49]
	v_cvt_pk_bf16_f32 v40, v40, v41
	v_pk_mul_f32 v[38:39], v[38:39], v[50:51]
	v_cvt_pk_bf16_f32 v41, v42, v43
	v_cvt_pk_bf16_f32 v42, v36, v37
	v_cndmask_b32_e64 v36, v61, v40, s[2:3]
	v_mov_b32_e32 v44, 0
	v_cvt_pk_bf16_f32 v43, v38, v39
	v_mov_b32_e32 v45, 0
	v_mov_b32_dpp v44, v36 row_ror:8 row_mask:0xf bank_mask:0xf
	v_cndmask_b32_e64 v36, v62, v41, s[2:3]
	v_mov_b32_e32 v47, 0
	v_cndmask_b32_e64 v37, v63, v42, s[2:3]
	v_mov_b32_dpp v45, v36 row_ror:8 row_mask:0xf bank_mask:0xf
	v_cndmask_b32_e64 v36, v64, v43, s[2:3]
	v_mov_b32_e32 v46, 0
	v_cndmask_b32_e64 v40, v40, v44, s[2:3]
	v_mov_b32_dpp v47, v36 row_ror:8 row_mask:0xf bank_mask:0xf
	v_cndmask_b32_e64 v36, v44, v61, s[2:3]
	v_cndmask_b32_e64 v44, v1, v76, s[2:3]
	v_mov_b32_dpp v46, v37 row_ror:8 row_mask:0xf bank_mask:0xf
	v_cndmask_b32_e64 v37, v45, v62, s[2:3]
	v_cndmask_b32_e64 v41, v41, v45, s[2:3]
	v_ashrrev_i32_e32 v45, 31, v44
	v_lshlrev_b64 v[44:45], 11, v[44:45]
	v_lshl_add_u64 v[44:45], s[68:69], 0, v[44:45]
	v_cndmask_b32_e64 v39, v47, v64, s[2:3]
	v_cndmask_b32_e64 v38, v46, v63, s[2:3]
	v_lshl_add_u64 v[44:45], v[44:45], 0, v[2:3]
	v_add_u32_e32 v1, 0x98, v184
	global_store_dwordx4 v[44:45], v[36:39], off
	v_add_u32_e32 v44, 0xb0, v184
	v_cndmask_b32_e64 v43, v43, v47, s[2:3]
	v_cndmask_b32_e64 v36, v76, v1, s[2:3]
	v_ashrrev_i32_e32 v37, 31, v36
	v_lshlrev_b64 v[36:37], 11, v[36:37]
	v_lshl_add_u64 v[36:37], s[68:69], 0, v[36:37]
	s_waitcnt vmcnt(1)
	v_lshlrev_b32_e32 v38, 16, v56
	v_cndmask_b32_e64 v42, v42, v46, s[2:3]
	v_lshl_add_u64 v[36:37], v[36:37], 0, v[2:3]
	v_ashrrev_i32_e32 v45, 31, v44
	v_max_f32_e32 v38, v38, v38
	v_and_b32_e32 v39, 0xffff0000, v56
	global_store_dwordx4 v[36:37], v[40:43], off
	v_lshlrev_b64 v[36:37], 12, v[44:45]
	v_max_f32_e32 v38, 0xc2700000, v38
	v_max_f32_e32 v39, v39, v39
	v_lshl_add_u64 v[36:37], s[38:39], 0, v[36:37]
	v_max_f32_e32 v39, 0xc2700000, v39
	v_mul_f32_e32 v38, 0xbfb8aa3b, v38
	v_lshl_add_u64 v[36:37], v[36:37], 0, v[140:141]
	v_exp_f32_e32 v45, v38
	v_mul_f32_e32 v38, 0xbfb8aa3b, v39
	v_exp_f32_e32 v47, v38
	global_load_dwordx4 v[40:43], v[36:37], off offset:2048
	s_nop 0
	global_load_dwordx4 v[36:39], v[36:37], off offset:2112
	v_add_f32_e32 v45, 1.0, v45
	v_rcp_f32_e32 v46, v45
	v_add_f32_e32 v45, 1.0, v47
	v_lshlrev_b32_e32 v47, 16, v57
	v_max_f32_e32 v47, v47, v47
	v_and_b32_e32 v48, 0xffff0000, v57
	v_max_f32_e32 v47, 0xc2700000, v47
	v_max_f32_e32 v48, v48, v48
	v_max_f32_e32 v48, 0xc2700000, v48
	v_mul_f32_e32 v47, 0xbfb8aa3b, v47
	v_exp_f32_e32 v49, v47
	v_mul_f32_e32 v47, 0xbfb8aa3b, v48
	v_exp_f32_e32 v50, v47
	v_rcp_f32_e32 v47, v45
	v_add_f32_e32 v45, 1.0, v49
	v_lshlrev_b32_e32 v49, 16, v58
	v_rcp_f32_e32 v48, v45
	v_add_f32_e32 v45, 1.0, v50
	v_max_f32_e32 v49, v49, v49
	v_and_b32_e32 v50, 0xffff0000, v58
	v_max_f32_e32 v49, 0xc2700000, v49
	v_max_f32_e32 v50, v50, v50
	v_max_f32_e32 v50, 0xc2700000, v50
	v_mul_f32_e32 v49, 0xbfb8aa3b, v49
	v_exp_f32_e32 v51, v49
	v_mul_f32_e32 v49, 0xbfb8aa3b, v50
	v_exp_f32_e32 v56, v49
	v_rcp_f32_e32 v49, v45
	v_add_f32_e32 v45, 1.0, v51
	v_lshlrev_b32_e32 v51, 16, v59
	v_rcp_f32_e32 v50, v45
	v_add_f32_e32 v45, 1.0, v56
	v_max_f32_e32 v51, v51, v51
	v_and_b32_e32 v56, 0xffff0000, v59
	v_max_f32_e32 v51, 0xc2700000, v51
	v_max_f32_e32 v56, v56, v56
	v_max_f32_e32 v56, 0xc2700000, v56
	v_mul_f32_e32 v51, 0xbfb8aa3b, v51
	v_exp_f32_e32 v57, v51
	v_mul_f32_e32 v51, 0xbfb8aa3b, v56
	v_exp_f32_e32 v58, v51
	v_rcp_f32_e32 v51, v45
	v_add_f32_e32 v45, 1.0, v57
	v_rcp_f32_e32 v56, v45
	v_add_f32_e32 v45, 1.0, v58
	v_rcp_f32_e32 v57, v45
	v_pk_mul_f32 v[28:29], v[28:29], v[50:51]
	v_pk_mul_f32 v[32:33], v[32:33], v[46:47]
	v_cvt_pk_bf16_f32 v47, v28, v29
	v_pk_mul_f32 v[30:31], v[30:31], v[56:57]
	v_lshlrev_b32_e32 v28, 16, v52
	v_and_b32_e32 v29, 0xffff0000, v52
	v_pk_mul_f32 v[34:35], v[34:35], v[48:49]
	v_cvt_pk_bf16_f32 v45, v32, v33
	v_max_f32_e32 v28, v28, v28
	v_max_f32_e32 v29, v29, v29
	v_cvt_pk_bf16_f32 v48, v30, v31
	v_lshlrev_b32_e32 v30, 16, v53
	v_and_b32_e32 v31, 0xffff0000, v53
	v_lshlrev_b32_e32 v32, 16, v54
	v_and_b32_e32 v33, 0xffff0000, v54
	v_cvt_pk_bf16_f32 v46, v34, v35
	v_max_f32_e32 v28, 0xc2700000, v28
	v_max_f32_e32 v29, 0xc2700000, v29
	v_max_f32_e32 v30, v30, v30
	v_max_f32_e32 v31, v31, v31
	v_max_f32_e32 v32, v32, v32
	v_max_f32_e32 v33, v33, v33
	v_lshlrev_b32_e32 v34, 16, v55
	v_and_b32_e32 v35, 0xffff0000, v55
	v_mul_f32_e32 v28, 0xbfb8aa3b, v28
	v_mul_f32_e32 v29, 0xbfb8aa3b, v29
	v_max_f32_e32 v30, 0xc2700000, v30
	v_max_f32_e32 v31, 0xc2700000, v31
	v_max_f32_e32 v32, 0xc2700000, v32
	v_max_f32_e32 v33, 0xc2700000, v33
	v_max_f32_e32 v34, v34, v34
	v_max_f32_e32 v35, v35, v35
	v_exp_f32_e32 v28, v28
	v_exp_f32_e32 v29, v29
	v_mul_f32_e32 v30, 0xbfb8aa3b, v30
	v_mul_f32_e32 v31, 0xbfb8aa3b, v31
	v_mul_f32_e32 v32, 0xbfb8aa3b, v32
	v_mul_f32_e32 v33, 0xbfb8aa3b, v33
	v_max_f32_e32 v34, 0xc2700000, v34
	v_max_f32_e32 v35, 0xc2700000, v35
	v_exp_f32_e32 v30, v30
	v_exp_f32_e32 v31, v31
	v_exp_f32_e32 v32, v32
	v_exp_f32_e32 v33, v33
	v_mul_f32_e32 v34, 0xbfb8aa3b, v34
	v_mul_f32_e32 v35, 0xbfb8aa3b, v35
	v_exp_f32_e32 v34, v34
	v_exp_f32_e32 v35, v35
	v_add_f32_e32 v28, 1.0, v28
	v_add_f32_e32 v29, 1.0, v29
	v_rcp_f32_e32 v28, v28
	v_rcp_f32_e32 v29, v29
	v_add_f32_e32 v30, 1.0, v30
	v_add_f32_e32 v31, 1.0, v31
	v_add_f32_e32 v32, 1.0, v32
	v_add_f32_e32 v33, 1.0, v33
	v_rcp_f32_e32 v30, v30
	v_rcp_f32_e32 v31, v31
	v_rcp_f32_e32 v32, v32
	v_rcp_f32_e32 v33, v33
	v_add_f32_e32 v34, 1.0, v34
	v_add_f32_e32 v35, 1.0, v35
	v_rcp_f32_e32 v34, v34
	v_rcp_f32_e32 v35, v35
	v_pk_mul_f32 v[24:25], v[24:25], v[28:29]
	v_pk_mul_f32 v[26:27], v[26:27], v[30:31]
	v_pk_mul_f32 v[20:21], v[20:21], v[32:33]
	v_cvt_pk_bf16_f32 v24, v24, v25
	v_pk_mul_f32 v[22:23], v[22:23], v[34:35]
	v_cvt_pk_bf16_f32 v25, v26, v27
	v_cvt_pk_bf16_f32 v26, v20, v21
	v_cndmask_b32_e64 v20, v45, v24, s[2:3]
	v_mov_b32_e32 v28, 0
	v_cvt_pk_bf16_f32 v27, v22, v23
	v_mov_b32_e32 v29, 0
	v_mov_b32_dpp v28, v20 row_ror:8 row_mask:0xf bank_mask:0xf
	v_cndmask_b32_e64 v20, v46, v25, s[2:3]
	v_mov_b32_e32 v31, 0
	v_cndmask_b32_e64 v21, v47, v26, s[2:3]
	v_mov_b32_dpp v29, v20 row_ror:8 row_mask:0xf bank_mask:0xf
	v_cndmask_b32_e64 v20, v48, v27, s[2:3]
	v_mov_b32_e32 v30, 0
	v_cndmask_b32_e64 v24, v24, v28, s[2:3]
	v_mov_b32_dpp v31, v20 row_ror:8 row_mask:0xf bank_mask:0xf
	v_cndmask_b32_e64 v20, v28, v45, s[2:3]
	v_cndmask_b32_e64 v28, v1, v60, s[2:3]
	v_mov_b32_dpp v30, v21 row_ror:8 row_mask:0xf bank_mask:0xf
	v_cndmask_b32_e64 v21, v29, v46, s[2:3]
	v_cndmask_b32_e64 v25, v25, v29, s[2:3]
	v_ashrrev_i32_e32 v29, 31, v28
	v_lshlrev_b64 v[28:29], 11, v[28:29]
	v_lshl_add_u64 v[28:29], s[68:69], 0, v[28:29]
	v_cndmask_b32_e64 v23, v31, v48, s[2:3]
	v_cndmask_b32_e64 v22, v30, v47, s[2:3]
	v_lshl_add_u64 v[28:29], v[28:29], 0, v[2:3]
	global_store_dwordx4 v[28:29], v[20:23], off
	v_add_u32_e32 v1, 0xa8, v184
	v_cndmask_b32_e64 v27, v27, v31, s[2:3]
	s_waitcnt vmcnt(1)
	v_lshlrev_b32_e32 v22, 16, v40
	v_and_b32_e32 v23, 0xffff0000, v40
	v_max_f32_e32 v22, v22, v22
	v_max_f32_e32 v23, v23, v23
	v_cndmask_b32_e64 v20, v60, v1, s[2:3]
	v_max_f32_e32 v22, 0xc2700000, v22
	v_max_f32_e32 v23, 0xc2700000, v23
	v_ashrrev_i32_e32 v21, 31, v20
	v_mul_f32_e32 v22, 0xbfb8aa3b, v22
	v_mul_f32_e32 v23, 0xbfb8aa3b, v23
	v_lshlrev_b64 v[20:21], 11, v[20:21]
	v_exp_f32_e32 v22, v22
	v_exp_f32_e32 v23, v23
	v_lshl_add_u64 v[20:21], s[68:69], 0, v[20:21]
	v_cndmask_b32_e64 v26, v26, v30, s[2:3]
	v_lshl_add_u64 v[20:21], v[20:21], 0, v[2:3]
	global_store_dwordx4 v[20:21], v[24:27], off
	v_add_f32_e32 v20, 1.0, v22
	v_add_f32_e32 v21, 1.0, v23
	v_lshlrev_b32_e32 v24, 16, v42
	v_and_b32_e32 v25, 0xffff0000, v42
	v_lshlrev_b32_e32 v22, 16, v41
	v_and_b32_e32 v23, 0xffff0000, v41
	v_max_f32_e32 v24, v24, v24
	v_max_f32_e32 v25, v25, v25
	v_lshlrev_b32_e32 v26, 16, v43
	v_and_b32_e32 v27, 0xffff0000, v43
	v_max_f32_e32 v22, v22, v22
	v_max_f32_e32 v23, v23, v23
	v_max_f32_e32 v24, 0xc2700000, v24
	v_max_f32_e32 v25, 0xc2700000, v25
	v_max_f32_e32 v26, v26, v26
	v_max_f32_e32 v27, v27, v27
	v_max_f32_e32 v22, 0xc2700000, v22
	v_max_f32_e32 v23, 0xc2700000, v23
	v_mul_f32_e32 v24, 0xbfb8aa3b, v24
	v_mul_f32_e32 v25, 0xbfb8aa3b, v25
	v_max_f32_e32 v26, 0xc2700000, v26
	v_max_f32_e32 v27, 0xc2700000, v27
	v_mul_f32_e32 v22, 0xbfb8aa3b, v22
	v_mul_f32_e32 v23, 0xbfb8aa3b, v23
	v_exp_f32_e32 v24, v24
	v_exp_f32_e32 v25, v25
	v_mul_f32_e32 v26, 0xbfb8aa3b, v26
	v_mul_f32_e32 v27, 0xbfb8aa3b, v27
	v_exp_f32_e32 v22, v22
	v_exp_f32_e32 v23, v23
	v_exp_f32_e32 v26, v26
	v_exp_f32_e32 v27, v27
	v_add_f32_e32 v24, 1.0, v24
	v_add_f32_e32 v25, 1.0, v25
	v_add_f32_e32 v22, 1.0, v22
	v_add_f32_e32 v23, 1.0, v23
	v_rcp_f32_e32 v24, v24
	v_rcp_f32_e32 v25, v25
	v_add_f32_e32 v26, 1.0, v26
	v_add_f32_e32 v27, 1.0, v27
	v_rcp_f32_e32 v20, v20
	v_rcp_f32_e32 v21, v21
	v_rcp_f32_e32 v22, v22
	v_rcp_f32_e32 v23, v23
	v_rcp_f32_e32 v26, v26
	v_rcp_f32_e32 v27, v27
	v_pk_mul_f32 v[12:13], v[12:13], v[24:25]
	v_pk_mul_f32 v[16:17], v[16:17], v[20:21]
	v_pk_mul_f32 v[18:19], v[18:19], v[22:23]
	v_pk_mul_f32 v[14:15], v[14:15], v[26:27]
	v_cvt_pk_bf16_f32 v22, v12, v13
	v_lshlrev_b32_e32 v12, 16, v36
	v_and_b32_e32 v13, 0xffff0000, v36
	v_cvt_pk_bf16_f32 v20, v16, v17
	v_max_f32_e32 v12, v12, v12
	v_max_f32_e32 v13, v13, v13
	v_cvt_pk_bf16_f32 v23, v14, v15
	v_lshlrev_b32_e32 v14, 16, v37
	v_and_b32_e32 v15, 0xffff0000, v37
	v_lshlrev_b32_e32 v16, 16, v38
	v_and_b32_e32 v17, 0xffff0000, v38
	v_cvt_pk_bf16_f32 v21, v18, v19
	v_max_f32_e32 v12, 0xc2700000, v12
	v_max_f32_e32 v13, 0xc2700000, v13
	v_max_f32_e32 v14, v14, v14
	v_max_f32_e32 v15, v15, v15
	v_max_f32_e32 v16, v16, v16
	v_max_f32_e32 v17, v17, v17
	v_lshlrev_b32_e32 v18, 16, v39
	v_and_b32_e32 v19, 0xffff0000, v39
	v_mul_f32_e32 v12, 0xbfb8aa3b, v12
	v_mul_f32_e32 v13, 0xbfb8aa3b, v13
	v_max_f32_e32 v14, 0xc2700000, v14
	v_max_f32_e32 v15, 0xc2700000, v15
	v_max_f32_e32 v16, 0xc2700000, v16
	v_max_f32_e32 v17, 0xc2700000, v17
	v_max_f32_e32 v18, v18, v18
	v_max_f32_e32 v19, v19, v19
	v_exp_f32_e32 v12, v12
	v_exp_f32_e32 v13, v13
	v_mul_f32_e32 v14, 0xbfb8aa3b, v14
	v_mul_f32_e32 v15, 0xbfb8aa3b, v15
	v_mul_f32_e32 v16, 0xbfb8aa3b, v16
	v_mul_f32_e32 v17, 0xbfb8aa3b, v17
	v_max_f32_e32 v18, 0xc2700000, v18
	v_max_f32_e32 v19, 0xc2700000, v19
	v_exp_f32_e32 v14, v14
	v_exp_f32_e32 v15, v15
	v_exp_f32_e32 v16, v16
	v_exp_f32_e32 v17, v17
	v_mul_f32_e32 v18, 0xbfb8aa3b, v18
	v_mul_f32_e32 v19, 0xbfb8aa3b, v19
	v_exp_f32_e32 v18, v18
	v_exp_f32_e32 v19, v19
	v_add_f32_e32 v12, 1.0, v12
	v_add_f32_e32 v13, 1.0, v13
	v_rcp_f32_e32 v12, v12
	v_rcp_f32_e32 v13, v13
	v_add_f32_e32 v14, 1.0, v14
	v_add_f32_e32 v15, 1.0, v15
	v_add_f32_e32 v16, 1.0, v16
	v_add_f32_e32 v17, 1.0, v17
	v_rcp_f32_e32 v14, v14
	v_rcp_f32_e32 v15, v15
	v_rcp_f32_e32 v16, v16
	v_rcp_f32_e32 v17, v17
	v_add_f32_e32 v18, 1.0, v18
	v_add_f32_e32 v19, 1.0, v19
	v_rcp_f32_e32 v18, v18
	v_rcp_f32_e32 v19, v19
	v_pk_mul_f32 v[8:9], v[8:9], v[12:13]
	v_pk_mul_f32 v[10:11], v[10:11], v[14:15]
	v_pk_mul_f32 v[4:5], v[4:5], v[16:17]
	v_cvt_pk_bf16_f32 v8, v8, v9
	v_pk_mul_f32 v[6:7], v[6:7], v[18:19]
	v_cvt_pk_bf16_f32 v9, v10, v11
	v_cvt_pk_bf16_f32 v10, v4, v5
	v_cndmask_b32_e64 v4, v20, v8, s[2:3]
	v_mov_b32_e32 v12, 0
	v_cvt_pk_bf16_f32 v11, v6, v7
	v_mov_b32_e32 v13, 0
	v_mov_b32_dpp v12, v4 row_ror:8 row_mask:0xf bank_mask:0xf
	v_cndmask_b32_e64 v4, v21, v9, s[2:3]
	v_mov_b32_e32 v15, 0
	v_cndmask_b32_e64 v5, v22, v10, s[2:3]
	v_mov_b32_dpp v13, v4 row_ror:8 row_mask:0xf bank_mask:0xf
	v_cndmask_b32_e64 v4, v23, v11, s[2:3]
	v_mov_b32_e32 v14, 0
	v_cndmask_b32_e64 v8, v8, v12, s[2:3]
	v_mov_b32_dpp v15, v4 row_ror:8 row_mask:0xf bank_mask:0xf
	v_cndmask_b32_e64 v4, v12, v20, s[2:3]
	v_cndmask_b32_e64 v12, v1, v44, s[2:3]
	v_mov_b32_dpp v14, v5 row_ror:8 row_mask:0xf bank_mask:0xf
	v_cndmask_b32_e64 v5, v13, v21, s[2:3]
	v_cndmask_b32_e64 v9, v9, v13, s[2:3]
	v_ashrrev_i32_e32 v13, 31, v12
	v_lshlrev_b64 v[12:13], 11, v[12:13]
	v_lshl_add_u64 v[12:13], s[68:69], 0, v[12:13]
	v_cndmask_b32_e64 v7, v15, v23, s[2:3]
	v_cndmask_b32_e64 v6, v14, v22, s[2:3]
	v_lshl_add_u64 v[12:13], v[12:13], 0, v[2:3]
	v_add_u32_e32 v1, 0xb8, v184
	global_store_dwordx4 v[12:13], v[4:7], off
	v_cndmask_b32_e64 v11, v11, v15, s[2:3]
	v_cndmask_b32_e64 v10, v10, v14, s[2:3]
	v_cndmask_b32_e64 v4, v44, v1, s[2:3]
	v_ashrrev_i32_e32 v5, 31, v4
	v_lshlrev_b64 v[4:5], 11, v[4:5]
	v_lshl_add_u64 v[4:5], s[68:69], 0, v[4:5]
	v_lshl_add_u64 v[2:3], v[4:5], 0, v[2:3]
	global_store_dwordx4 v[2:3], v[8:11], off
	s_cbranch_vccnz .LBB0_670
